# RWKV-7 chunk-record builder: the next unit's token-shift and first parameter loads also issued one unit ahead into spare registers
# baseline (speedup 1.0000x reference)
.LBB0_317:
	v_writelane_b32 v249, s0, 38
	s_and_b64 vcc, exec, s[2:3]
	s_nop 0
	v_writelane_b32 v249, s1, 39
	s_cbranch_vccz .LBB0_905
	s_cmp_eq_u32 s80, 4
	s_cselect_b64 s[0:1], -1, 0
	s_cmp_lg_u32 s80, 4
	s_cselect_b64 s[2:3], -1, 0
	v_writelane_b32 v249, s2, 40
	s_cmp_lt_u32 s8, 9
	s_cselect_b64 s[72:73], -1, 0
	v_writelane_b32 v249, s3, 41
	v_writelane_b32 v249, s0, 42
	s_mov_b64 s[46:47], 0x1000
	s_nop 0
	v_writelane_b32 v249, s1, 43
	s_and_b64 s[0:1], s[0:1], s[72:73]
	s_andn2_b64 vcc, exec, s[0:1]
	s_cbranch_vccnz .LBB0_486
	s_cmpk_gt_i32 s64, 0x8ff
	s_cbranch_scc1 .LBB0_342
	v_readlane_b32 s0, v249, 36
	s_lshl_b32 s8, s64, 2
	s_lshl_b32 s9, s0, 2
	s_mov_b32 s22, s64
	v_readlane_b32 s1, v249, 37
	s_mov_b32 s100, s8
	v_mbcnt_lo_u32_b32 v166, -1, 0
	v_mbcnt_hi_u32_b32 v166, -1, v166
	v_add_u32_e32 v167, s61, v166
	v_lshrrev_b32_e32 v168, 7, v167
	v_add_u32_e32 v168, s100, v168
	s_load_dwordx2 s[100:101], s[58:59], 0x158
	s_load_dwordx2 s[2:3], s[58:59], 0xb0
	s_load_dwordx2 s[4:5], s[58:59], 0xc8
	s_load_dwordx4 s[12:15], s[58:59], 0xe0
	s_load_dwordx2 s[20:21], s[58:59], 0xf0
	v_lshlrev_b32_e32 v169, 4, v168
	v_and_b32_e32 v169, 0x7f0, v169
	v_ashrrev_i32_e32 v170, 10, v168
	v_lshl_or_b32 v170, v170, 11, v169
	v_lshrrev_b32_e32 v171, 7, v168
	v_add_u32_e32 v172, 0xffffe000, v168
	v_and_b32_e32 v172, -8, v172
	v_add_u32_e32 v172, 0x4000, v172
	v_cmp_lt_i32_e32 vcc, 0x1fff, v168
	v_cndmask_b32_e32 v170, v170, v172, vcc
	v_cndmask_b32_e64 v169, v169, 0, vcc
	v_cndmask_b32_e32 v171, v171, v168, vcc
	v_mov_b32_e32 v173, 16
	v_cndmask_b32_e64 v173, v173, 8, vcc
	v_bfe_u32 v174, v167, 6, 1
	v_bfe_u32 v175, v166, 3, 3
	v_lshl_or_b32 v174, v174, 3, v175
	v_cmp_gt_u32_e32 vcc, v173, v174
	v_cndmask_b32_e32 v174, 0, v174, vcc
	v_lshlrev_b32_e32 v171, 6, v171
	v_and_b32_e32 v171, 0x1c0, v171
	v_lshlrev_b32_e32 v175, 3, v167
	v_and_b32_e32 v175, 56, v175
	v_or_b32_e32 v171, v171, v175
	v_add_u32_e32 v170, v170, v174
	v_or_b32_e32 v169, v169, v174
	v_lshlrev_b32_e32 v176, 1, v171
	v_mov_b32_e32 v177, 0
	v_mov_b32_e32 v178, 0xc00
	v_lshlrev_b32_e32 v242, 2, v171
	v_add_u32_e32 v243, 0x1000, v242
	s_waitcnt lgkmcnt(0)
	v_mov_b64_e32 v[180:181], s[100:101]
	v_mov_b64_e32 v[182:183], s[100:101]
	v_mad_i64_i32 v[180:181], vcc, v170, s83, v[180:181]
	v_mad_i64_i32 v[182:183], vcc, v170, v178, v[182:183]
	v_lshl_add_u64 v[180:181], v[180:181], 0, v[176:177]
	v_lshl_add_u64 v[182:183], v[182:183], 0, v[176:177]
	v_add_co_u32_e32 v180, vcc, 0x12f01000, v180
	v_addc_co_u32_e32 v181, vcc, 0, v181, vcc
	v_add_co_u32_e32 v182, vcc, 0x25600000, v182
	v_addc_co_u32_e32 v183, vcc, 0, v183, vcc
	v_cmp_eq_u32_e32 vcc, 0, v169
	v_cndmask_b32_e64 v185, -1, 0, vcc
	v_cndmask_b32_e64 v184, v205, 0, vcc
	v_lshl_add_u64 v[184:185], v[180:181], 0, v[184:185]
	global_load_dwordx4 v[128:131], v[182:183], off
	global_load_dwordx4 v[132:135], v[184:185], off
	global_load_dwordx4 v[136:139], v[184:185], off offset:1024
	global_load_dwordx4 v[140:143], v[180:181], off offset:1024
	global_load_dwordx4 v[144:147], v[180:181], off offset:2048
	global_load_dwordx4 v[148:151], v[180:181], off
	global_load_dwordx4 v[152:155], v[184:185], off offset:2048
	global_load_dwordx4 v[158:161], v[182:183], off offset:1024
	global_load_dwordx4 v[162:165], v[182:183], off offset:2048
	global_load_dwordx4 v[166:169], v242, s[2:3] offset:16
	global_load_dwordx4 v[170:173], v242, s[2:3]
	global_load_dwordx4 v[174:177], v242, s[2:3] offset:2064
	global_load_dwordx4 v[178:181], v242, s[2:3] offset:2048
	global_load_dwordx4 v[182:185], v243, s[2:3]
	global_load_dwordx4 v[186:189], v243, s[2:3] offset:16
	global_load_dwordx4 v[190:193], v242, s[4:5]
	global_load_dwordx4 v[222:225], v242, s[12:13]
	global_load_dwordx4 v[226:229], v242, s[14:15]
	global_load_dwordx4 v[230:233], v242, s[20:21]
	global_load_dwordx4 v[234:237], v242, s[4:5] offset:16
	global_load_dwordx4 v[238:241], v242, s[14:15] offset:16
	s_branch .LBB0_322

.LBB0_326:
	s_bfe_u32 s23, s23, 0x10006
	v_bfe_u32 v0, v107, 3, 3
	v_lshl_or_b32 v109, s23, 3, v0
	s_lshl_b32 s14, s26, 6
	v_lshlrev_b32_e32 v106, 3, v108
	v_cmp_gt_u32_e32 vcc, s7, v109
	s_and_b32 s14, s14, 0x1c0
	v_and_b32_e32 v88, 56, v106
	v_cndmask_b32_e32 v0, 0, v109, vcc
	v_or_b32_e32 v14, s14, v88
	v_add_u32_e32 v6, s25, v0
	v_or_b32_e32 v8, s24, v0
	s_waitcnt lgkmcnt(0)
	v_mov_b64_e32 v[0:1], s[4:5]
	v_mad_i64_i32 v[0:1], s[4:5], v6, s83, v[0:1]
	v_lshlrev_b32_e32 v156, 1, v14
	v_lshl_add_u64 v[0:1], v[0:1], 0, v[156:157]
	s_mov_b64 s[4:5], 0x12f01000
	v_lshl_add_u64 v[2:3], v[0:1], 0, s[4:5]
	v_mov_b64_e32 v[4:5], s[2:3]
	s_movk_i32 s2, 0xc00
	s_mov_b32 s4, 0x12f01000
	v_mad_i64_i32 v[4:5], s[2:3], v6, s2, v[4:5]
	v_add_co_u32_e32 v0, vcc, s4, v0
	v_lshl_add_u64 v[4:5], v[4:5], 0, v[156:157]
	s_mov_b64 s[2:3], 0x25600000
	v_addc_co_u32_e32 v1, vcc, 0, v1, vcc
	s_mov_b32 s4, 0x25600000
	v_lshl_add_u64 v[6:7], v[4:5], 0, s[2:3]
	v_cmp_eq_u32_e64 s[2:3], 0, v8
	v_add_co_u32_e32 v4, vcc, s4, v4
	s_nop 0
	v_cndmask_b32_e64 v9, -1, 0, s[2:3]
	v_cndmask_b32_e64 v8, v205, 0, s[2:3]
	v_addc_co_u32_e32 v5, vcc, 0, v5, vcc
	v_lshl_add_u64 v[12:13], v[2:3], 0, v[8:9]
	s_load_dwordx2 s[4:5], s[18:19], 0xb0
	v_lshlrev_b32_e32 v156, 2, v14
	s_nop 0
	s_waitcnt lgkmcnt(0)
	v_lshl_add_u64 v[4:5], s[4:5], 0, v[156:157]
	v_lshl_add_u64 v[6:7], v[4:5], 0, s[46:47]
	v_add_co_u32_e32 v4, vcc, 0x1000, v4
	v_cmp_le_u32_e64 s[4:5], s7, v109
	s_nop 0
	v_addc_co_u32_e32 v5, vcc, 0, v5, vcc
	s_nop 0
	s_and_b64 s[14:15], s[12:13], s[2:3]
	v_mov_b32_e32 v60, 0
	v_mov_b32_e32 v61, 0
	v_mov_b32_e32 v62, 0
	v_mov_b32_e32 v63, 0
	v_mov_b32_e32 v64, 0
	v_mov_b32_e32 v65, 0
	v_mov_b32_e32 v66, 0
	v_mov_b32_e32 v67, 0
	v_mov_b32_e32 v68, 0
	v_mov_b32_e32 v69, 0
	v_mov_b32_e32 v70, 0
	v_mov_b32_e32 v71, 0
	v_mov_b32_e32 v44, 0
	v_mov_b32_e32 v45, 0
	v_mov_b32_e32 v46, 0
	v_mov_b32_e32 v47, 0
	v_mov_b32_e32 v20, 0
	v_mov_b32_e32 v21, 0
	v_mov_b32_e32 v22, 0
	v_mov_b32_e32 v23, 0
	v_mov_b32_e32 v16, 0
	v_mov_b32_e32 v17, 0
	v_mov_b32_e32 v18, 0
	v_mov_b32_e32 v19, 0
	s_and_saveexec_b64 s[12:13], s[14:15]
	s_cbranch_execz .LBB0_328
	s_load_dwordx2 s[14:15], s[18:19], 0x30
	s_mul_hi_i32 s7, s1, 0x1c00
	s_mulk_i32 s1, 0x1c00
	s_waitcnt lgkmcnt(0)
	s_add_u32 s14, s14, s1
	s_addc_u32 s15, s15, s7
	v_lshl_add_u64 v[16:17], s[14:15], 0, v[156:157]
	global_load_dwordx4 v[60:63], v156, s[14:15]
	global_load_dwordx4 v[64:67], v156, s[14:15] offset:16
	global_load_dwordx4 v[68:71], v156, s[14:15] offset:2048
	global_load_dwordx4 v[44:47], v156, s[14:15] offset:2064
	v_lshl_add_u64 v[18:19], v[16:17], 0, s[46:47]
	v_add_co_u32_e32 v16, vcc, 0x1000, v16
	s_nop 1
	v_addc_co_u32_e32 v17, vcc, 0, v17, vcc
	global_load_dwordx4 v[20:23], v[16:17], off
	s_nop 0
	global_load_dwordx4 v[16:19], v[18:19], off offset:16
.LBB0_328:
	s_or_b64 exec, exec, s[12:13]
	s_load_dwordx2 s[24:25], s[18:19], 0xc8
	s_load_dwordx4 s[12:15], s[18:19], 0xe0
	s_waitcnt vmcnt(0)
	v_mov_b32_e32 v8, v128
	v_mov_b32_e32 v9, v129
	v_mov_b32_e32 v10, v130
	v_mov_b32_e32 v11, v131
	v_mov_b32_e32 v76, v132
	v_mov_b32_e32 v77, v133
	v_mov_b32_e32 v78, v134
	v_mov_b32_e32 v79, v135
	v_mov_b32_e32 v32, v136
	v_mov_b32_e32 v33, v137
	v_mov_b32_e32 v34, v138
	v_mov_b32_e32 v35, v139
	v_mov_b32_e32 v36, v140
	v_mov_b32_e32 v37, v141
	v_mov_b32_e32 v38, v142
	v_mov_b32_e32 v39, v143
	v_mov_b32_e32 v24, v144
	v_mov_b32_e32 v25, v145
	v_mov_b32_e32 v26, v146
	v_mov_b32_e32 v27, v147
	v_mov_b32_e32 v80, v148
	v_mov_b32_e32 v81, v149
	v_mov_b32_e32 v82, v150
	v_mov_b32_e32 v83, v151
	v_mov_b32_e32 v28, v152
	v_mov_b32_e32 v29, v153
	v_mov_b32_e32 v30, v154
	v_mov_b32_e32 v31, v155
	v_mov_b32_e32 v72, v158
	v_mov_b32_e32 v73, v159
	v_mov_b32_e32 v74, v160
	v_mov_b32_e32 v75, v161
	v_mov_b32_e32 v0, v162
	v_mov_b32_e32 v1, v163
	v_mov_b32_e32 v2, v164
	v_mov_b32_e32 v3, v165
	v_mov_b32_e32 v52, v166
	v_mov_b32_e32 v53, v167
	v_mov_b32_e32 v54, v168
	v_mov_b32_e32 v55, v169
	v_mov_b32_e32 v56, v170
	v_mov_b32_e32 v57, v171
	v_mov_b32_e32 v58, v172
	v_mov_b32_e32 v59, v173
	v_mov_b32_e32 v40, v174
	v_mov_b32_e32 v41, v175
	v_mov_b32_e32 v42, v176
	v_mov_b32_e32 v43, v177
	v_mov_b32_e32 v48, v178
	v_mov_b32_e32 v49, v179
	v_mov_b32_e32 v50, v180
	v_mov_b32_e32 v51, v181
	v_mov_b32_e32 v12, v182
	v_mov_b32_e32 v13, v183
	v_mov_b32_e32 v14, v184
	v_mov_b32_e32 v15, v185
	v_mov_b32_e32 v4, v186
	v_mov_b32_e32 v5, v187
	v_mov_b32_e32 v6, v188
	v_mov_b32_e32 v7, v189
	v_lshlrev_b32_e32 v110, 16, v80
	v_and_b32_e32 v111, 0xffff0000, v80
	v_lshlrev_b32_e32 v112, 16, v81
	v_and_b32_e32 v113, 0xffff0000, v81
	s_waitcnt lgkmcnt(0)
	v_mov_b32_e32 v84, v190
	v_mov_b32_e32 v85, v191
	v_mov_b32_e32 v86, v192
	v_mov_b32_e32 v87, v193
	v_mov_b32_e32 v94, v222
	v_mov_b32_e32 v95, v223
	v_mov_b32_e32 v96, v224
	v_mov_b32_e32 v97, v225
	s_load_dwordx2 s[20:21], s[18:19], 0xf0
	v_lshlrev_b32_e32 v114, 16, v82
	v_and_b32_e32 v115, 0xffff0000, v82
	v_lshlrev_b32_e32 v116, 16, v83
	v_and_b32_e32 v117, 0xffff0000, v83
	v_mov_b32_e32 v80, v226
	v_mov_b32_e32 v81, v227
	v_mov_b32_e32 v82, v228
	v_mov_b32_e32 v83, v229
	s_waitcnt lgkmcnt(0)
	v_mov_b32_e32 v98, v230
	v_mov_b32_e32 v99, v231
	v_mov_b32_e32 v100, v232
	v_mov_b32_e32 v101, v233
	v_lshlrev_b32_e32 v105, 16, v72
	v_and_b32_e32 v118, 0xffff0000, v72
	v_lshlrev_b32_e32 v119, 16, v73
	v_and_b32_e32 v120, 0xffff0000, v73
	v_lshlrev_b32_e32 v121, 16, v74
	v_and_b32_e32 v122, 0xffff0000, v74
	v_lshlrev_b32_e32 v123, 16, v75
	v_and_b32_e32 v124, 0xffff0000, v75
	v_mov_b32_e32 v72, v234
	v_mov_b32_e32 v73, v235
	v_mov_b32_e32 v74, v236
	v_mov_b32_e32 v75, v237
	v_and_b32_e32 v89, 0xffff0000, v76
	v_lshlrev_b32_e32 v90, 16, v77
	v_and_b32_e32 v91, 0xffff0000, v77
	v_lshlrev_b32_e32 v104, 16, v76
	v_cndmask_b32_e64 v104, v104, v60, s[2:3]
	v_cndmask_b32_e64 v89, v89, v61, s[2:3]
	v_cndmask_b32_e64 v90, v90, v62, s[2:3]
	v_cndmask_b32_e64 v91, v91, v63, s[2:3]
	v_mov_b32_e32 v60, v238
	v_mov_b32_e32 v61, v239
	v_mov_b32_e32 v62, v240
	v_mov_b32_e32 v63, v241
	v_lshlrev_b32_e32 v92, 16, v78
	v_and_b32_e32 v93, 0xffff0000, v78
	v_lshlrev_b32_e32 v102, 16, v79
	v_and_b32_e32 v103, 0xffff0000, v79
	v_and_b32_e32 v77, 0xffff0000, v36
	v_lshlrev_b32_e32 v76, 16, v36
	v_and_b32_e32 v36, 0xffff0000, v32
	v_lshlrev_b32_e32 v32, 16, v32
	v_and_b32_e32 v79, 0xffff0000, v37
	v_lshlrev_b32_e32 v78, 16, v37
	v_and_b32_e32 v37, 0xffff0000, v33
	v_lshlrev_b32_e32 v125, 16, v33
	v_cndmask_b32_e64 v92, v92, v64, s[2:3]
	v_cndmask_b32_e64 v93, v93, v65, s[2:3]
	v_cndmask_b32_e64 v102, v102, v66, s[2:3]
	v_cndmask_b32_e64 v103, v103, v67, s[2:3]
	v_cndmask_b32_e64 v33, v36, v69, s[2:3]
	v_cndmask_b32_e64 v32, v32, v68, s[2:3]
	v_cndmask_b32_e64 v37, v37, v71, s[2:3]
	v_cndmask_b32_e64 v36, v125, v70, s[2:3]
	global_load_dwordx4 v[64:67], v156, s[20:21] offset:16
	global_load_dwordx4 v[68:71], v156, s[12:13] offset:16
	v_pk_add_f32 v[32:33], v[32:33], v[76:77] neg_lo:[0,1] neg_hi:[0,1]
	v_sub_f32_e32 v102, v102, v116
	v_sub_f32_e32 v103, v103, v117
	v_pk_fma_f32 v[32:33], v[48:49], v[32:33], v[76:77]
	v_fmac_f32_e32 v116, v54, v102
	v_fmac_f32_e32 v117, v55, v103
	v_sub_f32_e32 v92, v92, v114
	v_sub_f32_e32 v93, v93, v115
	v_fmac_f32_e32 v114, v52, v92
	v_fmac_f32_e32 v115, v53, v93
	v_sub_f32_e32 v90, v90, v112
	v_sub_f32_e32 v91, v91, v113
	v_fmac_f32_e32 v112, v58, v90
	v_fmac_f32_e32 v113, v59, v91
	v_sub_f32_e32 v104, v104, v110
	v_sub_f32_e32 v89, v89, v111
	v_fmac_f32_e32 v110, v56, v104
	v_fmac_f32_e32 v111, v57, v89
	s_waitcnt vmcnt(7)
	v_add_f32_e32 v48, v84, v105
	v_add_f32_e32 v49, v85, v118
	v_mul_f32_e32 v54, 0xbfb8aa3b, v48
	v_mul_f32_e32 v55, 0xbfb8aa3b, v49
	v_exp_f32_e32 v54, v54
	v_exp_f32_e32 v55, v55
	v_add_f32_e32 v52, v86, v119
	v_add_f32_e32 v53, v87, v120
	v_mul_f32_e32 v52, 0xbfb8aa3b, v52
	v_mul_f32_e32 v53, 0xbfb8aa3b, v53
	v_exp_f32_e32 v52, v52
	v_exp_f32_e32 v53, v53
	v_add_f32_e32 v54, 1.0, v54
	v_add_f32_e32 v55, 1.0, v55
	v_rcp_f32_e32 v92, v54
	v_rcp_f32_e32 v93, v55
	v_add_f32_e32 v52, 1.0, v52
	v_add_f32_e32 v53, 1.0, v53
	s_waitcnt vmcnt(6)
	v_pk_mul_f32 v[90:91], v[32:33], v[94:95]
	v_rcp_f32_e32 v94, v52
	v_rcp_f32_e32 v95, v53
	v_pk_add_f32 v[52:53], v[92:93], -1.0 op_sel_hi:[1,0]
	v_pk_mul_f32 v[48:49], v[90:91], v[90:91]
	s_waitcnt vmcnt(5)
	v_pk_fma_f32 v[52:53], v[80:81], v[52:53], 1.0 op_sel_hi:[1,1,0]
	v_lshlrev_b32_e32 v118, 6, v109
	v_pk_mul_f32 v[80:81], v[32:33], v[52:53]
	s_nop 0
	v_mul_f32_e32 v32, v110, v80
	v_mul_f32_e32 v33, v111, v81
	s_waitcnt vmcnt(4)
	v_fma_f32 v52, v98, v32, 0
	v_fmac_f32_e32 v52, v99, v33
	v_pk_add_f32 v[32:33], v[36:37], v[78:79] neg_lo:[0,1] neg_hi:[0,1]
	v_pk_add_f32 v[36:37], v[94:95], -1.0 op_sel_hi:[1,0]
	v_pk_fma_f32 v[32:33], v[50:51], v[32:33], v[78:79]
	v_pk_fma_f32 v[36:37], v[82:83], v[36:37], 1.0 op_sel_hi:[1,1,0]
	s_waitcnt vmcnt(3)
	v_add_f32_e32 v50, v73, v122
	v_pk_mul_f32 v[82:83], v[32:33], v[36:37]
	v_add_f32_e32 v37, v72, v121
	v_mul_f32_e32 v37, 0xbfb8aa3b, v37
	v_exp_f32_e32 v37, v37
	v_mul_f32_e32 v50, 0xbfb8aa3b, v50
	v_exp_f32_e32 v50, v50
	v_mul_f32_e32 v36, v112, v82
	v_fmac_f32_e32 v52, v100, v36
	v_mul_f32_e32 v36, v113, v83
	v_fmac_f32_e32 v52, v101, v36
	v_add_f32_e32 v36, 1.0, v37
	v_rcp_f32_e32 v98, v36
	v_add_f32_e32 v36, 1.0, v50
	v_rcp_f32_e32 v99, v36
	v_and_b32_e32 v37, 0xffff0000, v38
	v_lshlrev_b32_e32 v36, 16, v38
	v_and_b32_e32 v38, 0xffff0000, v34
	v_lshlrev_b32_e32 v34, 16, v34
	v_cndmask_b32_e64 v45, v38, v45, s[2:3]
	v_cndmask_b32_e64 v44, v34, v44, s[2:3]
	v_pk_add_f32 v[44:45], v[44:45], v[36:37] neg_lo:[0,1] neg_hi:[0,1]
	v_add_f32_e32 v38, v74, v123
	v_pk_fma_f32 v[36:37], v[40:41], v[44:45], v[36:37]
	v_pk_add_f32 v[40:41], v[98:99], -1.0 op_sel_hi:[1,0]
	v_mul_f32_e32 v38, 0xbfb8aa3b, v38
	s_waitcnt vmcnt(2)
	v_pk_fma_f32 v[40:41], v[60:61], v[40:41], 1.0 op_sel_hi:[1,1,0]
	v_exp_f32_e32 v38, v38
	v_pk_mul_f32 v[84:85], v[36:37], v[40:41]
	v_add_f32_e32 v40, v75, v124
	v_mul_f32_e32 v40, 0xbfb8aa3b, v40
	v_exp_f32_e32 v40, v40
	v_mul_f32_e32 v34, v114, v84
	s_waitcnt vmcnt(1)
	v_fmac_f32_e32 v52, v64, v34
	v_mul_f32_e32 v34, v115, v85
	v_fmac_f32_e32 v52, v65, v34
	v_add_f32_e32 v34, 1.0, v38
	v_rcp_f32_e32 v102, v34
	v_add_f32_e32 v34, 1.0, v40
	v_rcp_f32_e32 v103, v34
	v_and_b32_e32 v34, 0xffff0000, v35
	v_lshlrev_b32_e32 v38, 16, v35
	v_and_b32_e32 v41, 0xffff0000, v39
	v_lshlrev_b32_e32 v40, 16, v39
	v_cndmask_b32_e64 v35, v34, v47, s[2:3]
	v_cndmask_b32_e64 v34, v38, v46, s[2:3]
	v_pk_add_f32 v[34:35], v[34:35], v[40:41] neg_lo:[0,1] neg_hi:[0,1]
	v_pk_add_f32 v[38:39], v[102:103], -1.0 op_sel_hi:[1,0]
	v_pk_fma_f32 v[34:35], v[42:43], v[34:35], v[40:41]
	v_pk_fma_f32 v[38:39], v[62:63], v[38:39], 1.0 op_sel_hi:[1,1,0]
	v_pk_mul_f32 v[96:97], v[32:33], v[96:97]
	v_pk_mul_f32 v[86:87], v[34:35], v[38:39]
	v_pk_mul_f32 v[32:33], v[96:97], v[96:97]
	v_mul_f32_e32 v38, v116, v86
	v_fmac_f32_e32 v52, v66, v38
	v_add_f32_e32 v38, v48, v49
	s_waitcnt vmcnt(0)
	v_pk_mul_f32 v[100:101], v[36:37], v[68:69]
	v_add_f32_e32 v32, v32, v38
	v_pk_mul_f32 v[36:37], v[100:101], v[100:101]
	v_add_f32_e32 v32, v33, v32
	v_pk_mul_f32 v[104:105], v[34:35], v[70:71]
	v_add_f32_e32 v32, v32, v36
	v_pk_mul_f32 v[34:35], v[104:105], v[104:105]
	v_add_f32_e32 v32, v37, v32
	v_add_f32_e32 v32, v34, v32
	v_add_f32_e32 v32, v35, v32
	v_mul_f32_e32 v33, v117, v87
	v_fmac_f32_e32 v52, v67, v33
	v_add_f32_dpp v32, v32, v32 quad_perm:[1,0,3,2] row_mask:0xf bank_mask:0xf bound_ctrl:1
	s_nop 1
	v_add_f32_dpp v89, v32, v32 quad_perm:[2,3,0,1] row_mask:0xf bank_mask:0xf bound_ctrl:1
	v_add_f32_dpp v32, v52, v52 quad_perm:[1,0,3,2] row_mask:0xf bank_mask:0xf bound_ctrl:1
	s_nop 0
	v_mov_b32_dpp v119, v89 row_half_mirror row_mask:0xf bank_mask:0xf bound_ctrl:1
	v_add_f32_dpp v120, v32, v32 quad_perm:[2,3,0,1] row_mask:0xf bank_mask:0xf bound_ctrl:1
	s_nop 1
	v_mov_b32_dpp v121, v120 row_half_mirror row_mask:0xf bank_mask:0xf bound_ctrl:1
	s_and_saveexec_b64 s[12:13], s[4:5]
	s_xor_b64 s[4:5], exec, s[12:13]
	v_lshlrev_b32_e32 v118, 6, v109
	s_or_saveexec_b64 s[12:13], s[4:5]
	s_ashr_i32 s7, s6, 31
	v_mov_b32_e32 v55, 1.0
	v_mov_b32_e32 v63, 0
	v_lshlrev_b32_e32 v88, 2, v88
	v_mov_b32_e32 v62, 0
	v_mov_b32_e32 v61, 0
	v_mov_b32_e32 v60, 0
	v_mov_b32_e32 v67, 0
	v_mov_b32_e32 v66, 0
	v_mov_b32_e32 v65, 0
	v_mov_b32_e32 v64, 0
	v_mov_b32_e32 v59, 0
	v_mov_b32_e32 v58, 0
	v_mov_b32_e32 v57, 0
	v_mov_b32_e32 v56, 0
	v_mov_b32_e32 v75, 0
	v_mov_b32_e32 v74, 0
	v_mov_b32_e32 v73, 0
	v_mov_b32_e32 v72, 0
	v_mov_b32_e32 v54, 1.0
	v_mov_b32_e32 v53, 1.0
	v_mov_b32_e32 v52, 1.0
	v_mov_b32_e32 v48, 1.0
	v_mov_b32_e32 v49, 1.0
	v_mov_b32_e32 v50, 1.0
	v_mov_b32_e32 v51, 1.0
	v_mov_b32_e32 v70, 0
	v_mov_b32_e32 v71, 0
	v_mov_b32_e32 v68, 0
	v_mov_b32_e32 v69, 0
	v_mov_b32_e32 v78, 0
	v_mov_b32_e32 v79, 0
	v_mov_b32_e32 v76, 0
	v_mov_b32_e32 v77, 0
	v_mov_b32_e32 v34, 0
	v_mov_b32_e32 v35, 0
	v_mov_b32_e32 v32, 0
	v_mov_b32_e32 v33, 0
	v_mov_b32_e32 v42, 0
	v_mov_b32_e32 v43, 0
	v_mov_b32_e32 v40, 0
	v_mov_b32_e32 v41, 0
	v_mov_b32_e32 v38, 0
	v_mov_b32_e32 v39, 0
	v_mov_b32_e32 v36, 0
	v_mov_b32_e32 v37, 0
	v_mov_b32_e32 v46, 0
	v_mov_b32_e32 v47, 0
	v_mov_b32_e32 v44, 0
	v_mov_b32_e32 v45, 0
	s_xor_b64 exec, exec, s[12:13]
	s_cbranch_execz .LBB0_332
	s_load_dwordx2 s[4:5], s[18:19], 0xb8
	v_add_f32_e32 v32, v89, v119
	s_mov_b32 s1, 0xf800000
	v_mul_f32_e32 v33, 0x4f800000, v32
	v_cmp_gt_f32_e32 vcc, s1, v32
	s_waitcnt lgkmcnt(0)
	global_load_dwordx4 v[48:51], v156, s[4:5] offset:16
	global_load_dwordx4 v[52:55], v156, s[4:5]
	v_cndmask_b32_e32 v32, v32, v33, vcc
	v_sqrt_f32_e32 v33, v32
	v_and_b32_e32 v57, 0xffff0000, v11
	v_lshlrev_b32_e32 v66, 16, v11
	v_and_b32_e32 v67, 0xffff0000, v10
	v_add_u32_e32 v11, -1, v33
	v_add_u32_e32 v34, 1, v33
	v_fma_f32 v35, -v11, v33, v32
	v_fma_f32 v36, -v34, v33, v32
	v_cmp_ge_f32_e64 s[4:5], 0, v35
	v_lshlrev_b32_e32 v68, 16, v10
	v_and_b32_e32 v64, 0xffff0000, v31
	v_cndmask_b32_e64 v11, v33, v11, s[4:5]
	v_cmp_lt_f32_e64 s[4:5], 0, v36
	v_lshlrev_b32_e32 v65, 16, v31
	v_and_b32_e32 v60, 0xffff0000, v30
	v_cndmask_b32_e64 v11, v11, v34, s[4:5]
	v_mul_f32_e32 v33, 0x37800000, v11
	v_cndmask_b32_e32 v11, v11, v33, vcc
	v_cmp_class_f32_e32 vcc, v32, v196
	v_lshlrev_b32_e32 v61, 16, v30
	v_and_b32_e32 v31, 0xffff0000, v25
	v_cndmask_b32_e32 v11, v11, v32, vcc
	v_max_f32_e32 v11, 0x2b8cbccc, v11
	v_div_scale_f32 v32, s[4:5], v11, v11, 1.0
	v_rcp_f32_e32 v33, v32
	v_div_scale_f32 v10, vcc, 1.0, v11, 1.0
	v_lshlrev_b32_e32 v30, 16, v25
	v_fma_f32 v34, -v32, v33, 1.0
	v_fmac_f32_e32 v33, v34, v33
	v_mul_f32_e32 v34, v10, v33
	v_fma_f32 v35, -v32, v34, v10
	v_fmac_f32_e32 v34, v35, v33
	v_fma_f32 v10, -v32, v34, v10
	v_div_fmas_f32 v10, v10, v33, v34
	v_div_fixup_f32 v10, v10, v11, 1.0
	v_pk_mul_f32 v[32:33], v[104:105], v[10:11] op_sel_hi:[1,0]
	v_pk_mul_f32 v[40:41], v[100:101], v[10:11] op_sel_hi:[1,0]
	v_pk_mul_f32 v[42:43], v[96:97], v[10:11] op_sel_hi:[1,0]
	v_pk_mul_f32 v[10:11], v[90:91], v[10:11] op_sel_hi:[1,0]
	v_pk_mul_f32 v[38:39], v[102:103], v[32:33]
	v_pk_add_f32 v[34:35], v[32:33], 0 neg_lo:[1,1] neg_hi:[1,1]
	v_pk_mul_f32 v[36:37], v[98:99], v[40:41]
	v_pk_add_f32 v[32:33], v[40:41], 0 neg_lo:[1,1] neg_hi:[1,1]
	v_pk_mul_f32 v[44:45], v[92:93], v[10:11]
	v_pk_add_f32 v[40:41], v[10:11], 0 neg_lo:[1,1] neg_hi:[1,1]
	v_and_b32_e32 v25, 0xffff0000, v28
	v_lshlrev_b32_e32 v56, 16, v28
	v_and_b32_e32 v58, 0xffff0000, v29
	v_lshlrev_b32_e32 v59, 16, v29
	v_and_b32_e32 v29, 0xffff0000, v24
	v_lshlrev_b32_e32 v28, 16, v24
	v_add_f32_e32 v24, v120, v121
	v_and_b32_e32 v63, 0xffff0000, v27
	v_lshlrev_b32_e32 v62, 16, v27
	v_and_b32_e32 v27, 0xffff0000, v26
	v_lshlrev_b32_e32 v26, 16, v26
	v_lshlrev_b32_e32 v156, 8, v109
	v_mov_b32_e32 v89, v157
	v_pk_mul_f32 v[46:47], v[94:95], v[42:43]
	v_pk_add_f32 v[42:43], v[42:43], 0 neg_lo:[1,1] neg_hi:[1,1]
	v_mov_b32_e32 v75, v113
	v_mov_b32_e32 v74, v112
	v_mov_b32_e32 v73, v111
	v_mov_b32_e32 v72, v110
	v_mov_b32_e32 v70, v86
	v_mov_b32_e32 v71, v87
	v_mov_b32_e32 v69, v85
	v_mov_b32_e32 v78, v82
	v_mov_b32_e32 v79, v83
	v_mov_b32_e32 v76, v80
	v_mov_b32_e32 v77, v81
	s_waitcnt vmcnt(1)
	v_add_f32_e32 v10, v51, v57
	v_add_f32_e32 v11, v50, v66
	v_mul_f32_e32 v50, 0xbfb8aa3b, v10
	v_exp_f32_e32 v50, v50
	v_mul_f32_e32 v51, 0xbfb8aa3b, v11
	v_add_f32_e32 v49, v49, v67
	v_exp_f32_e32 v51, v51
	v_add_f32_e32 v50, 1.0, v50
	v_log_f32_e32 v50, v50
	v_mul_f32_e32 v57, 0xbfb8aa3b, v49
	v_cmp_gt_f32_e32 vcc, s95, v10
	v_exp_f32_e32 v57, v57
	v_mul_f32_e32 v50, 0x3f317218, v50
	v_cndmask_b32_e64 v10, v50, -v10, vcc
	v_sub_f32_e32 v10, -0.5, v10
	v_add_f32_e32 v48, v48, v68
	v_add_f32_e32 v51, 1.0, v51
	v_mul_f32_e32 v10, 0x3fb8aa3b, v10
	v_mul_f32_e32 v66, 0xbfb8aa3b, v48
	v_log_f32_e32 v51, v51
	v_exp_f32_e32 v10, v10
	v_add_f32_e32 v57, 1.0, v57
	v_exp_f32_e32 v66, v66
	v_log_f32_e32 v57, v57
	v_mul_f32_e32 v51, 0x3f317218, v51
	v_cmp_gt_f32_e32 vcc, s95, v11
	v_mul_f32_e32 v10, 0xbfb8aa3b, v10
	v_mul_f32_e32 v57, 0x3f317218, v57
	v_cndmask_b32_e64 v11, v51, -v11, vcc
	v_exp_f32_e32 v51, v10
	v_add_f32_e32 v10, 1.0, v66
	v_cmp_gt_f32_e32 vcc, s95, v49
	v_log_f32_e32 v10, v10
	v_sub_f32_e32 v11, -0.5, v11
	v_cndmask_b32_e64 v49, v57, -v49, vcc
	v_sub_f32_e32 v49, -0.5, v49
	v_mul_f32_e32 v11, 0x3fb8aa3b, v11
	v_mul_f32_e32 v49, 0x3fb8aa3b, v49
	v_exp_f32_e32 v11, v11
	v_exp_f32_e32 v49, v49
	v_mul_f32_e32 v10, 0x3f317218, v10
	v_cmp_gt_f32_e32 vcc, s95, v48
	v_mul_f32_e32 v11, 0xbfb8aa3b, v11
	v_exp_f32_e32 v50, v11
	v_cndmask_b32_e64 v10, v10, -v48, vcc
	v_sub_f32_e32 v10, -0.5, v10
	v_and_b32_e32 v48, 0xffff0000, v9
	v_mul_f32_e32 v10, 0x3fb8aa3b, v10
	s_waitcnt vmcnt(0)
	v_add_f32_e32 v55, v55, v48
	v_lshlrev_b32_e32 v9, 16, v9
	v_mul_f32_e32 v11, 0xbfb8aa3b, v49
	v_exp_f32_e32 v10, v10
	v_mul_f32_e32 v48, 0xbfb8aa3b, v55
	v_add_f32_e32 v9, v54, v9
	v_exp_f32_e32 v57, v48
	v_exp_f32_e32 v49, v11
	v_mul_f32_e32 v11, 0xbfb8aa3b, v9
	v_exp_f32_e32 v11, v11
	v_mul_f32_e32 v10, 0xbfb8aa3b, v10
	v_exp_f32_e32 v48, v10
	v_add_f32_e32 v10, 1.0, v57
	v_log_f32_e32 v10, v10
	v_add_f32_e32 v11, 1.0, v11
	v_log_f32_e32 v11, v11
	v_cmp_gt_f32_e32 vcc, s95, v55
	v_mul_f32_e32 v10, 0x3f317218, v10
	v_mov_b32_e32 v67, v117
	v_cndmask_b32_e64 v10, v10, -v55, vcc
	v_mul_f32_e32 v11, 0x3f317218, v11
	v_cmp_gt_f32_e32 vcc, s95, v9
	v_sub_f32_e32 v10, -0.5, v10
	v_mul_f32_e32 v10, 0x3fb8aa3b, v10
	v_cndmask_b32_e64 v9, v11, -v9, vcc
	v_and_b32_e32 v11, 0xffff0000, v8
	v_add_f32_e32 v11, v53, v11
	v_exp_f32_e32 v10, v10
	v_mul_f32_e32 v53, 0xbfb8aa3b, v11
	v_exp_f32_e32 v53, v53
	v_lshlrev_b32_e32 v8, 16, v8
	v_mul_f32_e32 v10, 0xbfb8aa3b, v10
	v_exp_f32_e32 v55, v10
	v_add_f32_e32 v10, 1.0, v53
	v_add_f32_e32 v8, v52, v8
	v_log_f32_e32 v10, v10
	v_mul_f32_e32 v52, 0xbfb8aa3b, v8
	v_exp_f32_e32 v52, v52
	v_cmp_gt_f32_e32 vcc, s95, v11
	v_mul_f32_e32 v10, 0x3f317218, v10
	v_sub_f32_e32 v9, -0.5, v9
	v_cndmask_b32_e64 v10, v10, -v11, vcc
	v_add_f32_e32 v11, 1.0, v52
	v_log_f32_e32 v11, v11
	v_cmp_gt_f32_e32 vcc, s95, v8
	v_mul_f32_e32 v9, 0x3fb8aa3b, v9
	v_sub_f32_e32 v10, -0.5, v10
	v_mul_f32_e32 v11, 0x3f317218, v11
	v_cndmask_b32_e64 v8, v11, -v8, vcc
	v_sub_f32_e32 v8, -0.5, v8
	v_exp_f32_e32 v9, v9
	v_mul_f32_e32 v10, 0x3fb8aa3b, v10
	v_mul_f32_e32 v8, 0x3fb8aa3b, v8
	v_exp_f32_e32 v10, v10
	v_exp_f32_e32 v8, v8
	v_mul_f32_e32 v9, 0xbfb8aa3b, v9
	v_exp_f32_e32 v54, v9
	v_mul_f32_e32 v9, 0xbfb8aa3b, v10
	v_mul_f32_e32 v8, 0xbfb8aa3b, v8
	v_exp_f32_e32 v53, v9
	v_exp_f32_e32 v52, v8
	v_cndmask_b32_e64 v9, v25, v21, s[2:3]
	v_cndmask_b32_e64 v8, v56, v20, s[2:3]
	v_pk_add_f32 v[8:9], v[8:9], v[28:29] neg_lo:[0,1] neg_hi:[0,1]
	v_mov_b32_e32 v66, v116
	v_pk_fma_f32 v[56:57], v[12:13], v[8:9], v[28:29]
	v_mov_b32_e32 v68, v84
	v_pk_mul_f32 v[8:9], v[56:57], v[24:25] op_sel_hi:[1,0]
	s_nop 0
	v_and_b32_sdwa v10, v9, v195 dst_sel:DWORD dst_unused:UNUSED_PAD src0_sel:WORD_1 src1_sel:DWORD
	v_and_b32_sdwa v11, v8, v195 dst_sel:DWORD dst_unused:UNUSED_PAD src0_sel:WORD_1 src1_sel:DWORD
	v_add3_u32 v9, v9, v10, s54
	v_add3_u32 v8, v8, v11, s54
	v_cndmask_b32_e64 v11, v58, v23, s[2:3]
	v_cndmask_b32_e64 v10, v59, v22, s[2:3]
	v_pk_add_f32 v[10:11], v[10:11], v[30:31] neg_lo:[0,1] neg_hi:[0,1]
	v_and_b32_e32 v9, 0xffff0000, v9
	v_pk_fma_f32 v[58:59], v[14:15], v[10:11], v[30:31]
	v_and_b32_e32 v8, 0xffff0000, v8
	v_pk_mul_f32 v[10:11], v[58:59], v[24:25] op_sel_hi:[1,0]
	v_or_b32_sdwa v9, v9, v0 dst_sel:DWORD dst_unused:UNUSED_PAD src0_sel:DWORD src1_sel:WORD_1
	v_or_b32_sdwa v8, v8, v0 dst_sel:DWORD dst_unused:UNUSED_PAD src0_sel:DWORD src1_sel:WORD_0
	v_and_b32_sdwa v0, v11, v195 dst_sel:DWORD dst_unused:UNUSED_PAD src0_sel:WORD_1 src1_sel:DWORD
	v_and_b32_sdwa v12, v10, v195 dst_sel:DWORD dst_unused:UNUSED_PAD src0_sel:WORD_1 src1_sel:DWORD
	v_add3_u32 v0, v11, v0, s54
	v_add3_u32 v10, v10, v12, s54
	v_and_b32_e32 v0, 0xffff0000, v0
	v_and_b32_e32 v10, 0xffff0000, v10
	v_or_b32_sdwa v11, v0, v1 dst_sel:DWORD dst_unused:UNUSED_PAD src0_sel:DWORD src1_sel:WORD_1
	v_or_b32_sdwa v10, v10, v1 dst_sel:DWORD dst_unused:UNUSED_PAD src0_sel:DWORD src1_sel:WORD_0
	v_cndmask_b32_e64 v1, v60, v17, s[2:3]
	v_cndmask_b32_e64 v0, v61, v16, s[2:3]
	v_pk_add_f32 v[0:1], v[0:1], v[26:27] neg_lo:[0,1] neg_hi:[0,1]
	s_nop 0
	v_pk_fma_f32 v[60:61], v[4:5], v[0:1], v[26:27]
	s_nop 0
	v_pk_mul_f32 v[0:1], v[60:61], v[24:25] op_sel_hi:[1,0]
	s_nop 0
	v_and_b32_sdwa v4, v1, v195 dst_sel:DWORD dst_unused:UNUSED_PAD src0_sel:WORD_1 src1_sel:DWORD
	v_and_b32_sdwa v5, v0, v195 dst_sel:DWORD dst_unused:UNUSED_PAD src0_sel:WORD_1 src1_sel:DWORD
	v_add3_u32 v1, v1, v4, s54
	v_add3_u32 v0, v0, v5, s54
	v_and_b32_e32 v1, 0xffff0000, v1
	v_and_b32_e32 v0, 0xffff0000, v0
	v_or_b32_sdwa v5, v1, v2 dst_sel:DWORD dst_unused:UNUSED_PAD src0_sel:DWORD src1_sel:WORD_1
	v_or_b32_sdwa v4, v0, v2 dst_sel:DWORD dst_unused:UNUSED_PAD src0_sel:DWORD src1_sel:WORD_0
	v_cndmask_b32_e64 v1, v64, v19, s[2:3]
	v_cndmask_b32_e64 v0, v65, v18, s[2:3]
	v_pk_add_f32 v[0:1], v[0:1], v[62:63] neg_lo:[0,1] neg_hi:[0,1]
	s_lshl_b64 s[2:3], s[6:7], 12
	v_pk_fma_f32 v[62:63], v[6:7], v[0:1], v[62:63]
	s_add_u32 s2, s16, s2
	v_pk_mul_f32 v[0:1], v[62:63], v[24:25] op_sel_hi:[1,0]
	s_addc_u32 s3, s17, s3
	v_and_b32_sdwa v2, v1, v195 dst_sel:DWORD dst_unused:UNUSED_PAD src0_sel:WORD_1 src1_sel:DWORD
	v_and_b32_sdwa v6, v0, v195 dst_sel:DWORD dst_unused:UNUSED_PAD src0_sel:WORD_1 src1_sel:DWORD
	v_add3_u32 v1, v1, v2, s54
	v_add3_u32 v0, v0, v6, s54
	v_and_b32_e32 v1, 0xffff0000, v1
	v_and_b32_e32 v0, 0xffff0000, v0
	v_or_b32_sdwa v7, v1, v3 dst_sel:DWORD dst_unused:UNUSED_PAD src0_sel:DWORD src1_sel:WORD_1
	v_or_b32_sdwa v6, v0, v3 dst_sel:DWORD dst_unused:UNUSED_PAD src0_sel:DWORD src1_sel:WORD_0
	v_lshl_add_u64 v[0:1], s[2:3], 0, v[156:157]
	v_lshl_add_u64 v[0:1], v[0:1], 0, v[88:89]
	s_mov_b64 s[2:3], 0x34800000
	v_lshl_add_u64 v[2:3], v[0:1], 0, s[2:3]
	v_add_co_u32_e32 v0, vcc, s96, v0
	v_mov_b32_e32 v65, v115
	s_nop 0
	v_addc_co_u32_e32 v1, vcc, 0, v1, vcc
	v_mov_b32_e32 v64, v114
	global_store_dwordx4 v[0:1], v[8:11], off
	global_store_dwordx4 v[2:3], v[4:7], off offset:16
.LBB0_332:
	s_or_b64 exec, exec, s[12:13]
	s_add_i32 s100, s8, s9
	s_cmpk_ge_i32 s100, 0x2400
	s_cbranch_scc1 .Lr1pf_skip
	v_mbcnt_lo_u32_b32 v166, -1, 0
	v_mbcnt_hi_u32_b32 v166, -1, v166
	v_add_u32_e32 v167, s61, v166
	v_lshrrev_b32_e32 v168, 7, v167
	v_add_u32_e32 v168, s100, v168
	s_load_dwordx2 s[100:101], s[58:59], 0x158
	s_load_dwordx2 s[2:3], s[58:59], 0xb0
	s_load_dwordx2 s[4:5], s[58:59], 0xc8
	s_load_dwordx4 s[12:15], s[58:59], 0xe0
	s_load_dwordx2 s[20:21], s[58:59], 0xf0
	v_lshlrev_b32_e32 v169, 4, v168
	v_and_b32_e32 v169, 0x7f0, v169
	v_ashrrev_i32_e32 v170, 10, v168
	v_lshl_or_b32 v170, v170, 11, v169
	v_lshrrev_b32_e32 v171, 7, v168
	v_add_u32_e32 v172, 0xffffe000, v168
	v_and_b32_e32 v172, -8, v172
	v_add_u32_e32 v172, 0x4000, v172
	v_cmp_lt_i32_e32 vcc, 0x1fff, v168
	v_cndmask_b32_e32 v170, v170, v172, vcc
	v_cndmask_b32_e64 v169, v169, 0, vcc
	v_cndmask_b32_e32 v171, v171, v168, vcc
	v_mov_b32_e32 v173, 16
	v_cndmask_b32_e64 v173, v173, 8, vcc
	v_bfe_u32 v174, v167, 6, 1
	v_bfe_u32 v175, v166, 3, 3
	v_lshl_or_b32 v174, v174, 3, v175
	v_cmp_gt_u32_e32 vcc, v173, v174
	v_cndmask_b32_e32 v174, 0, v174, vcc
	v_lshlrev_b32_e32 v171, 6, v171
	v_and_b32_e32 v171, 0x1c0, v171
	v_lshlrev_b32_e32 v175, 3, v167
	v_and_b32_e32 v175, 56, v175
	v_or_b32_e32 v171, v171, v175
	v_add_u32_e32 v170, v170, v174
	v_or_b32_e32 v169, v169, v174
	v_lshlrev_b32_e32 v176, 1, v171
	v_mov_b32_e32 v177, 0
	v_mov_b32_e32 v178, 0xc00
	v_lshlrev_b32_e32 v242, 2, v171
	v_add_u32_e32 v243, 0x1000, v242
	s_waitcnt lgkmcnt(0)
	v_mov_b64_e32 v[180:181], s[100:101]
	v_mov_b64_e32 v[182:183], s[100:101]
	v_mad_i64_i32 v[180:181], vcc, v170, s83, v[180:181]
	v_mad_i64_i32 v[182:183], vcc, v170, v178, v[182:183]
	v_lshl_add_u64 v[180:181], v[180:181], 0, v[176:177]
	v_lshl_add_u64 v[182:183], v[182:183], 0, v[176:177]
	v_add_co_u32_e32 v180, vcc, 0x12f01000, v180
	v_addc_co_u32_e32 v181, vcc, 0, v181, vcc
	v_add_co_u32_e32 v182, vcc, 0x25600000, v182
	v_addc_co_u32_e32 v183, vcc, 0, v183, vcc
	v_cmp_eq_u32_e32 vcc, 0, v169
	v_cndmask_b32_e64 v185, -1, 0, vcc
	v_cndmask_b32_e64 v184, v205, 0, vcc
	v_lshl_add_u64 v[184:185], v[180:181], 0, v[184:185]
	global_load_dwordx4 v[128:131], v[182:183], off
	global_load_dwordx4 v[132:135], v[184:185], off
	global_load_dwordx4 v[136:139], v[184:185], off offset:1024
	global_load_dwordx4 v[140:143], v[180:181], off offset:1024
	global_load_dwordx4 v[144:147], v[180:181], off offset:2048
	global_load_dwordx4 v[148:151], v[180:181], off
	global_load_dwordx4 v[152:155], v[184:185], off offset:2048
	global_load_dwordx4 v[158:161], v[182:183], off offset:1024
	global_load_dwordx4 v[162:165], v[182:183], off offset:2048
	global_load_dwordx4 v[166:169], v242, s[2:3] offset:16
	global_load_dwordx4 v[170:173], v242, s[2:3]
	global_load_dwordx4 v[174:177], v242, s[2:3] offset:2064
	global_load_dwordx4 v[178:181], v242, s[2:3] offset:2048
	global_load_dwordx4 v[182:185], v243, s[2:3]
	global_load_dwordx4 v[186:189], v243, s[2:3] offset:16
	global_load_dwordx4 v[190:193], v242, s[4:5]
	global_load_dwordx4 v[222:225], v242, s[12:13]
	global_load_dwordx4 v[226:229], v242, s[14:15]
	global_load_dwordx4 v[230:233], v242, s[20:21]
	global_load_dwordx4 v[234:237], v242, s[4:5] offset:16
	global_load_dwordx4 v[238:241], v242, s[14:15] offset:16
